# cache policy: nt hint on the SB/SWA mixer y stores (on top of v54)
# baseline (speedup 1.0000x reference)
; DI unsigned cvtpk(float lo, float hi) { typedef float f2 __attribute__((ext_vector_type(2))); typedef __bf16 b2 __attribute__((ext_vector_type(2))); f2 v = {lo, hi}; b2 b = __builtin_convertvector(v, b2); return __builtin_bit_cast(unsigned, b); }
; DI float bflo(unsigned w) { return __uint_as_float(w << 16); }
; DI float bfhi(unsigned w) { return __uint_as_float(w & 0xffff0000u); }
; DI float silu_(float g) { return g * fast_rcp(1.f + fast_exp2(-g * LOG2E)); }
; DI void write_y(const f32x16& o0, const f32x16& o1, float scale, const bf16_t* grow, bf16_t* yrow, int h) {
; #pragma unroll
;     for (int dh = 0; dh < 2; ++dh) {
;         u32x2 w[4];
; #pragma unroll
;         for (int grp = 0; grp < 4; ++grp) {
;             const int d0 = 32 * dh + 8 * grp + 4 * h;
;             const u32x2 g = *(const u32x2*)(grow + d0);
;             const f32x16& o = dh ? o1 : o0;
;             const float y0 = o[4 * grp + 0] * scale * silu_(bflo(g.x)), y1 = o[4 * grp + 1] * scale * silu_(bfhi(g.x));
;             const float y2 = o[4 * grp + 2] * scale * silu_(bflo(g.y)), y3 = o[4 * grp + 3] * scale * silu_(bfhi(g.y));
;             w[grp].x = cvtpk(y0, y1); w[grp].y = cvtpk(y2, y3);
;         }
;         store_pair16(yrow + 32 * dh, w[0], w[1], 0, h);
;         store_pair16(yrow + 32 * dh, w[2], w[3], 1, h);
;     }
; __global__ void __launch_bounds__(512, 2) hybrid_fwd(Params p) {
;     ...
;             for (int u = wg; u < 1024; u += G) {
.LBB0_333:
	s_add_i32 s17, s17, s78
	s_cmpk_gt_i32 s17, 0x3ff
	s_waitcnt vmcnt(0)
	v_lshlrev_b32_e32 v58, 16, v160
	v_and_b32_e32 v59, 0xffff0000, v160
	v_lshlrev_b32_e32 v60, 16, v161
	v_and_b32_e32 v61, 0xffff0000, v161
	v_mul_f32_e32 v62, 0xbfb8aa3b, v58
	v_mul_f32_e32 v63, 0xbfb8aa3b, v59
	v_mul_f32_e32 v64, 0xbfb8aa3b, v60
	v_mul_f32_e32 v65, 0xbfb8aa3b, v61
	v_exp_f32_e32 v62, v62
	v_exp_f32_e32 v63, v63
	v_exp_f32_e32 v64, v64
	v_exp_f32_e32 v65, v65
	v_add_f32_e32 v62, 1.0, v62
	v_add_f32_e32 v63, 1.0, v63
	v_add_f32_e32 v64, 1.0, v64
	v_add_f32_e32 v65, 1.0, v65
	v_rcp_f32_e32 v62, v62
	v_rcp_f32_e32 v63, v63
	v_rcp_f32_e32 v64, v64
	v_rcp_f32_e32 v65, v65
	v_mul_f32_e32 v58, v62, v58
	v_mul_f32_e32 v59, v63, v59
	v_mul_f32_e32 v60, v64, v60
	v_mul_f32_e32 v61, v65, v61
	v_mul_f32_e32 v18, v18, v58
	v_mul_f32_e32 v19, v19, v59
	v_mul_f32_e32 v20, v20, v60
	v_mul_f32_e32 v21, v21, v61
	v_cvt_pk_bf16_f32 v18, v18, v19
	v_cvt_pk_bf16_f32 v19, v20, v21
	v_lshlrev_b32_e32 v58, 16, v162
	v_and_b32_e32 v59, 0xffff0000, v162
	v_lshlrev_b32_e32 v60, 16, v163
	v_and_b32_e32 v61, 0xffff0000, v163
	v_mul_f32_e32 v62, 0xbfb8aa3b, v58
	v_mul_f32_e32 v63, 0xbfb8aa3b, v59
	v_mul_f32_e32 v64, 0xbfb8aa3b, v60
	v_mul_f32_e32 v65, 0xbfb8aa3b, v61
	v_exp_f32_e32 v62, v62
	v_exp_f32_e32 v63, v63
	v_exp_f32_e32 v64, v64
	v_exp_f32_e32 v65, v65
	v_add_f32_e32 v62, 1.0, v62
	v_add_f32_e32 v63, 1.0, v63
	v_add_f32_e32 v64, 1.0, v64
	v_add_f32_e32 v65, 1.0, v65
	v_rcp_f32_e32 v62, v62
	v_rcp_f32_e32 v63, v63
	v_rcp_f32_e32 v64, v64
	v_rcp_f32_e32 v65, v65
	v_mul_f32_e32 v58, v62, v58
	v_mul_f32_e32 v59, v63, v59
	v_mul_f32_e32 v60, v64, v60
	v_mul_f32_e32 v61, v65, v61
	v_mul_f32_e32 v22, v22, v58
	v_mul_f32_e32 v23, v23, v59
	v_mul_f32_e32 v24, v24, v60
	v_mul_f32_e32 v25, v25, v61
	v_cvt_pk_bf16_f32 v20, v22, v23
	v_cvt_pk_bf16_f32 v21, v24, v25
	s_nop 1
	v_permlane32_swap_b32_e32 v18, v20
	v_permlane32_swap_b32_e32 v19, v21
	global_store_dwordx4 v[84:85], v[18:21], off nt
	v_lshlrev_b32_e32 v58, 16, v164
	v_and_b32_e32 v59, 0xffff0000, v164
	v_lshlrev_b32_e32 v60, 16, v165
	v_and_b32_e32 v61, 0xffff0000, v165
	v_mul_f32_e32 v62, 0xbfb8aa3b, v58
	v_mul_f32_e32 v63, 0xbfb8aa3b, v59
	v_mul_f32_e32 v64, 0xbfb8aa3b, v60
	v_mul_f32_e32 v65, 0xbfb8aa3b, v61
	v_exp_f32_e32 v62, v62
	v_exp_f32_e32 v63, v63
	v_exp_f32_e32 v64, v64
	v_exp_f32_e32 v65, v65
	v_add_f32_e32 v62, 1.0, v62
	v_add_f32_e32 v63, 1.0, v63
	v_add_f32_e32 v64, 1.0, v64
	v_add_f32_e32 v65, 1.0, v65
	v_rcp_f32_e32 v62, v62
	v_rcp_f32_e32 v63, v63
	v_rcp_f32_e32 v64, v64
	v_rcp_f32_e32 v65, v65
	v_mul_f32_e32 v58, v62, v58
	v_mul_f32_e32 v59, v63, v59
	v_mul_f32_e32 v60, v64, v60
	v_mul_f32_e32 v61, v65, v61
	v_mul_f32_e32 v26, v26, v58
	v_mul_f32_e32 v27, v27, v59
	v_mul_f32_e32 v28, v28, v60
	v_mul_f32_e32 v29, v29, v61
	v_cvt_pk_bf16_f32 v26, v26, v27
	v_cvt_pk_bf16_f32 v27, v28, v29
	v_lshlrev_b32_e32 v58, 16, v166
	v_and_b32_e32 v59, 0xffff0000, v166
	v_lshlrev_b32_e32 v60, 16, v167
	v_and_b32_e32 v61, 0xffff0000, v167
	v_mul_f32_e32 v62, 0xbfb8aa3b, v58
	v_mul_f32_e32 v63, 0xbfb8aa3b, v59
	v_mul_f32_e32 v64, 0xbfb8aa3b, v60
	v_mul_f32_e32 v65, 0xbfb8aa3b, v61
	v_exp_f32_e32 v62, v62
	v_exp_f32_e32 v63, v63
	v_exp_f32_e32 v64, v64
	v_exp_f32_e32 v65, v65
	v_add_f32_e32 v62, 1.0, v62
	v_add_f32_e32 v63, 1.0, v63
	v_add_f32_e32 v64, 1.0, v64
	v_add_f32_e32 v65, 1.0, v65
	v_rcp_f32_e32 v62, v62
	v_rcp_f32_e32 v63, v63
	v_rcp_f32_e32 v64, v64
	v_rcp_f32_e32 v65, v65
	v_mul_f32_e32 v58, v62, v58
	v_mul_f32_e32 v59, v63, v59
	v_mul_f32_e32 v60, v64, v60
	v_mul_f32_e32 v61, v65, v61
	v_mul_f32_e32 v30, v30, v58
	v_mul_f32_e32 v31, v31, v59
	v_mul_f32_e32 v32, v32, v60
	v_mul_f32_e32 v33, v33, v61
	v_cvt_pk_bf16_f32 v28, v30, v31
	v_cvt_pk_bf16_f32 v29, v32, v33
	s_nop 1
	v_permlane32_swap_b32_e32 v26, v28
	v_permlane32_swap_b32_e32 v27, v29
; DI unsigned cvtpk(float lo, float hi) { typedef float f2 __attribute__((ext_vector_type(2))); typedef __bf16 b2 __attribute__((ext_vector_type(2))); f2 v = {lo, hi}; b2 b = __builtin_convertvector(v, b2); return __builtin_bit_cast(unsigned, b); }
; DI float bflo(unsigned w) { return __uint_as_float(w << 16); }
; DI float bfhi(unsigned w) { return __uint_as_float(w & 0xffff0000u); }
; DI float silu_(float g) { return g * fast_rcp(1.f + fast_exp2(-g * LOG2E)); }
; DI void write_y(const f32x16& o0, const f32x16& o1, float scale, const bf16_t* grow, bf16_t* yrow, int h) {
; #pragma unroll
;     for (int dh = 0; dh < 2; ++dh) {
;         u32x2 w[4];
; #pragma unroll
;         for (int grp = 0; grp < 4; ++grp) {
;             const int d0 = 32 * dh + 8 * grp + 4 * h;
;             const u32x2 g = *(const u32x2*)(grow + d0);
;             const f32x16& o = dh ? o1 : o0;
;             const float y0 = o[4 * grp + 0] * scale * silu_(bflo(g.x)), y1 = o[4 * grp + 1] * scale * silu_(bfhi(g.x));
;             const float y2 = o[4 * grp + 2] * scale * silu_(bflo(g.y)), y3 = o[4 * grp + 3] * scale * silu_(bfhi(g.y));
;             w[grp].x = cvtpk(y0, y1); w[grp].y = cvtpk(y2, y3);
;         }
;         store_pair16(yrow + 32 * dh, w[0], w[1], 0, h);
;         store_pair16(yrow + 32 * dh, w[2], w[3], 1, h);
;     }
	global_store_dwordx4 v[84:85], v[26:29], off offset:32 nt
	v_lshlrev_b32_e32 v58, 16, v168
	v_and_b32_e32 v59, 0xffff0000, v168
	v_lshlrev_b32_e32 v60, 16, v169
	v_and_b32_e32 v61, 0xffff0000, v169
	v_mul_f32_e32 v62, 0xbfb8aa3b, v58
	v_mul_f32_e32 v63, 0xbfb8aa3b, v59
	v_mul_f32_e32 v64, 0xbfb8aa3b, v60
	v_mul_f32_e32 v65, 0xbfb8aa3b, v61
	v_exp_f32_e32 v62, v62
	v_exp_f32_e32 v63, v63
	v_exp_f32_e32 v64, v64
	v_exp_f32_e32 v65, v65
	v_add_f32_e32 v62, 1.0, v62
	v_add_f32_e32 v63, 1.0, v63
	v_add_f32_e32 v64, 1.0, v64
	v_add_f32_e32 v65, 1.0, v65
	v_rcp_f32_e32 v62, v62
	v_rcp_f32_e32 v63, v63
	v_rcp_f32_e32 v64, v64
	v_rcp_f32_e32 v65, v65
	v_mul_f32_e32 v58, v62, v58
	v_mul_f32_e32 v59, v63, v59
	v_mul_f32_e32 v60, v64, v60
	v_mul_f32_e32 v61, v65, v61
	v_mul_f32_e32 v2, v2, v58
	v_mul_f32_e32 v3, v3, v59
	v_mul_f32_e32 v4, v4, v60
	v_mul_f32_e32 v5, v5, v61
	v_cvt_pk_bf16_f32 v2, v2, v3
	v_cvt_pk_bf16_f32 v3, v4, v5
	v_lshlrev_b32_e32 v58, 16, v170
	v_and_b32_e32 v59, 0xffff0000, v170
	v_lshlrev_b32_e32 v60, 16, v171
	v_and_b32_e32 v61, 0xffff0000, v171
	v_mul_f32_e32 v62, 0xbfb8aa3b, v58
	v_mul_f32_e32 v63, 0xbfb8aa3b, v59
	v_mul_f32_e32 v64, 0xbfb8aa3b, v60
	v_mul_f32_e32 v65, 0xbfb8aa3b, v61
	v_exp_f32_e32 v62, v62
	v_exp_f32_e32 v63, v63
	v_exp_f32_e32 v64, v64
	v_exp_f32_e32 v65, v65
	v_add_f32_e32 v62, 1.0, v62
	v_add_f32_e32 v63, 1.0, v63
	v_add_f32_e32 v64, 1.0, v64
	v_add_f32_e32 v65, 1.0, v65
	v_rcp_f32_e32 v62, v62
	v_rcp_f32_e32 v63, v63
	v_rcp_f32_e32 v64, v64
	v_rcp_f32_e32 v65, v65
	v_mul_f32_e32 v58, v62, v58
	v_mul_f32_e32 v59, v63, v59
	v_mul_f32_e32 v60, v64, v60
	v_mul_f32_e32 v61, v65, v61
	v_mul_f32_e32 v6, v6, v58
	v_mul_f32_e32 v7, v7, v59
	v_mul_f32_e32 v8, v8, v60
	v_mul_f32_e32 v9, v9, v61
	v_cvt_pk_bf16_f32 v4, v6, v7
	v_cvt_pk_bf16_f32 v5, v8, v9
	s_nop 1
	v_permlane32_swap_b32_e32 v2, v4
	v_permlane32_swap_b32_e32 v3, v5
	global_store_dwordx4 v[84:85], v[2:5], off offset:64 nt
	v_lshlrev_b32_e32 v58, 16, v172
	v_and_b32_e32 v59, 0xffff0000, v172
	v_lshlrev_b32_e32 v60, 16, v173
	v_and_b32_e32 v61, 0xffff0000, v173
	v_mul_f32_e32 v62, 0xbfb8aa3b, v58
	v_mul_f32_e32 v63, 0xbfb8aa3b, v59
	v_mul_f32_e32 v64, 0xbfb8aa3b, v60
	v_mul_f32_e32 v65, 0xbfb8aa3b, v61
	v_exp_f32_e32 v62, v62
	v_exp_f32_e32 v63, v63
	v_exp_f32_e32 v64, v64
	v_exp_f32_e32 v65, v65
	v_add_f32_e32 v62, 1.0, v62
	v_add_f32_e32 v63, 1.0, v63
	v_add_f32_e32 v64, 1.0, v64
	v_add_f32_e32 v65, 1.0, v65
	v_rcp_f32_e32 v62, v62
	v_rcp_f32_e32 v63, v63
	v_rcp_f32_e32 v64, v64
	v_rcp_f32_e32 v65, v65
	v_mul_f32_e32 v58, v62, v58
	v_mul_f32_e32 v59, v63, v59
	v_mul_f32_e32 v60, v64, v60
	v_mul_f32_e32 v61, v65, v61
	v_mul_f32_e32 v10, v10, v58
	v_mul_f32_e32 v11, v11, v59
	v_mul_f32_e32 v12, v12, v60
	v_mul_f32_e32 v13, v13, v61
	v_cvt_pk_bf16_f32 v10, v10, v11
	v_cvt_pk_bf16_f32 v11, v12, v13
	v_lshlrev_b32_e32 v58, 16, v174
	v_and_b32_e32 v59, 0xffff0000, v174
	v_lshlrev_b32_e32 v60, 16, v175
	v_and_b32_e32 v61, 0xffff0000, v175
	v_mul_f32_e32 v62, 0xbfb8aa3b, v58
	v_mul_f32_e32 v63, 0xbfb8aa3b, v59
	v_mul_f32_e32 v64, 0xbfb8aa3b, v60
	v_mul_f32_e32 v65, 0xbfb8aa3b, v61
	v_exp_f32_e32 v62, v62
	v_exp_f32_e32 v63, v63
	v_exp_f32_e32 v64, v64
	v_exp_f32_e32 v65, v65
	v_add_f32_e32 v62, 1.0, v62
	v_add_f32_e32 v63, 1.0, v63
	v_add_f32_e32 v64, 1.0, v64
	v_add_f32_e32 v65, 1.0, v65
	v_rcp_f32_e32 v62, v62
	v_rcp_f32_e32 v63, v63
	v_rcp_f32_e32 v64, v64
	v_rcp_f32_e32 v65, v65
	v_mul_f32_e32 v58, v62, v58
	v_mul_f32_e32 v59, v63, v59
	v_mul_f32_e32 v60, v64, v60
	v_mul_f32_e32 v61, v65, v61
	v_mul_f32_e32 v14, v14, v58
	v_mul_f32_e32 v15, v15, v59
	v_mul_f32_e32 v16, v16, v60
	v_mul_f32_e32 v17, v17, v61
	v_cvt_pk_bf16_f32 v12, v14, v15
	v_cvt_pk_bf16_f32 v13, v16, v17
	s_nop 1
	v_permlane32_swap_b32_e32 v10, v12
	v_permlane32_swap_b32_e32 v11, v13
	global_store_dwordx4 v[84:85], v[10:13], off offset:96 nt
	s_cbranch_scc1 .LBB0_358

; DI unsigned cvtpk(float lo, float hi) { typedef float f2 __attribute__((ext_vector_type(2))); typedef __bf16 b2 __attribute__((ext_vector_type(2))); f2 v = {lo, hi}; b2 b = __builtin_convertvector(v, b2); return __builtin_bit_cast(unsigned, b); }
; DI float bflo(unsigned w) { return __uint_as_float(w << 16); }
; DI float bfhi(unsigned w) { return __uint_as_float(w & 0xffff0000u); }
; DI float fast_rcp(float x) { return __builtin_amdgcn_rcpf(x); }
; DI float xhalf_sum(float v) { auto rr = __builtin_amdgcn_permlane32_swap(__float_as_uint(v), __float_as_uint(v), false, false); return __uint_as_float(rr[0]) + __uint_as_float(rr[1]); }
; DI float silu_(float g) { return g * fast_rcp(1.f + fast_exp2(-g * LOG2E)); }
; DI void write_y(const f32x16& o0, const f32x16& o1, float scale, const bf16_t* grow, bf16_t* yrow, int h) {
; #pragma unroll
;     for (int dh = 0; dh < 2; ++dh) {
;         u32x2 w[4];
; #pragma unroll
;         for (int grp = 0; grp < 4; ++grp) {
;             const int d0 = 32 * dh + 8 * grp + 4 * h;
;             const u32x2 g = *(const u32x2*)(grow + d0);
;             const f32x16& o = dh ? o1 : o0;
;             const float y0 = o[4 * grp + 0] * scale * silu_(bflo(g.x)), y1 = o[4 * grp + 1] * scale * silu_(bfhi(g.x));
;             const float y2 = o[4 * grp + 2] * scale * silu_(bflo(g.y)), y3 = o[4 * grp + 3] * scale * silu_(bfhi(g.y));
;             w[grp].x = cvtpk(y0, y1); w[grp].y = cvtpk(y2, y3);
;         }
;         store_pair16(yrow + 32 * dh, w[0], w[1], 0, h);
;         store_pair16(yrow + 32 * dh, w[2], w[3], 1, h);
;     }
; DI void swa_wg_unit(bf16_t* act, int b, int hk, int Qb, const float* sinks_l, LAS const float* tabS, LAS unsigned char* lds, int wid, int lane) {
;     ...
;         l = xhalf_sum(l);
;         write_y(o0, o1, fast_rcp(l), act + rowq * PITCH + C_GC + hq * 64, act + rowq * PITCH + C_QC + hq * 64, h);
.LBB0_377:
	s_lshl_b32 s10, s10, 6
	s_lshl_b32 s38, s10, 1
	v_mov_b32_e32 v0, v118
	s_nop 1
	v_permlane32_swap_b32_e32 v118, v0
	v_add_f32_e32 v0, v118, v0
	v_rcp_f32_e32 v0, v0
	s_add_i32 s13, s13, 1
	s_cmp_eq_u32 s13, 4
	s_waitcnt vmcnt(0)
	v_lshlrev_b32_e32 v64, 16, v160
	v_and_b32_e32 v65, 0xffff0000, v160
	v_lshlrev_b32_e32 v66, 16, v161
	v_and_b32_e32 v67, 0xffff0000, v161
	v_mul_f32_e32 v68, 0xbfb8aa3b, v64
	v_mul_f32_e32 v69, 0xbfb8aa3b, v65
	v_mul_f32_e32 v70, 0xbfb8aa3b, v66
	v_mul_f32_e32 v71, 0xbfb8aa3b, v67
	v_exp_f32_e32 v68, v68
	v_exp_f32_e32 v69, v69
	v_exp_f32_e32 v70, v70
	v_exp_f32_e32 v71, v71
	v_add_f32_e32 v68, 1.0, v68
	v_add_f32_e32 v69, 1.0, v69
	v_add_f32_e32 v70, 1.0, v70
	v_add_f32_e32 v71, 1.0, v71
	v_rcp_f32_e32 v68, v68
	v_rcp_f32_e32 v69, v69
	v_rcp_f32_e32 v70, v70
	v_rcp_f32_e32 v71, v71
	v_mul_f32_e32 v64, v68, v64
	v_mul_f32_e32 v65, v69, v65
	v_mul_f32_e32 v66, v70, v66
	v_mul_f32_e32 v67, v71, v67
	v_mul_f32_e32 v32, v32, v0
	v_mul_f32_e32 v33, v33, v0
	v_mul_f32_e32 v34, v34, v0
	v_mul_f32_e32 v35, v35, v0
	v_mul_f32_e32 v32, v32, v64
	v_mul_f32_e32 v33, v33, v65
	v_mul_f32_e32 v34, v34, v66
	v_mul_f32_e32 v35, v35, v67
	v_cvt_pk_bf16_f32 v32, v32, v33
	v_cvt_pk_bf16_f32 v33, v34, v35
	v_lshlrev_b32_e32 v64, 16, v162
	v_and_b32_e32 v65, 0xffff0000, v162
	v_lshlrev_b32_e32 v66, 16, v163
	v_and_b32_e32 v67, 0xffff0000, v163
	v_mul_f32_e32 v68, 0xbfb8aa3b, v64
	v_mul_f32_e32 v69, 0xbfb8aa3b, v65
	v_mul_f32_e32 v70, 0xbfb8aa3b, v66
	v_mul_f32_e32 v71, 0xbfb8aa3b, v67
	v_exp_f32_e32 v68, v68
	v_exp_f32_e32 v69, v69
	v_exp_f32_e32 v70, v70
	v_exp_f32_e32 v71, v71
	v_add_f32_e32 v68, 1.0, v68
	v_add_f32_e32 v69, 1.0, v69
	v_add_f32_e32 v70, 1.0, v70
	v_add_f32_e32 v71, 1.0, v71
	v_rcp_f32_e32 v68, v68
	v_rcp_f32_e32 v69, v69
	v_rcp_f32_e32 v70, v70
	v_rcp_f32_e32 v71, v71
	v_mul_f32_e32 v64, v68, v64
	v_mul_f32_e32 v65, v69, v65
	v_mul_f32_e32 v66, v70, v66
	v_mul_f32_e32 v67, v71, v67
	v_mul_f32_e32 v36, v36, v0
	v_mul_f32_e32 v37, v37, v0
	v_mul_f32_e32 v38, v38, v0
	v_mul_f32_e32 v39, v39, v0
	v_mul_f32_e32 v36, v36, v64
	v_mul_f32_e32 v37, v37, v65
	v_mul_f32_e32 v38, v38, v66
	v_mul_f32_e32 v39, v39, v67
	v_cvt_pk_bf16_f32 v34, v36, v37
	v_cvt_pk_bf16_f32 v35, v38, v39
	s_nop 1
	v_permlane32_swap_b32_e32 v32, v34
	v_permlane32_swap_b32_e32 v33, v35
	global_store_dwordx4 v[104:105], v[32:35], off nt
	v_lshlrev_b32_e32 v64, 16, v164
	v_and_b32_e32 v65, 0xffff0000, v164
	v_lshlrev_b32_e32 v66, 16, v165
	v_and_b32_e32 v67, 0xffff0000, v165
	v_mul_f32_e32 v68, 0xbfb8aa3b, v64
	v_mul_f32_e32 v69, 0xbfb8aa3b, v65
	v_mul_f32_e32 v70, 0xbfb8aa3b, v66
	v_mul_f32_e32 v71, 0xbfb8aa3b, v67
	v_exp_f32_e32 v68, v68
	v_exp_f32_e32 v69, v69
	v_exp_f32_e32 v70, v70
	v_exp_f32_e32 v71, v71
	v_add_f32_e32 v68, 1.0, v68
	v_add_f32_e32 v69, 1.0, v69
	v_add_f32_e32 v70, 1.0, v70
	v_add_f32_e32 v71, 1.0, v71
	v_rcp_f32_e32 v68, v68
	v_rcp_f32_e32 v69, v69
	v_rcp_f32_e32 v70, v70
	v_rcp_f32_e32 v71, v71
	v_mul_f32_e32 v64, v68, v64
	v_mul_f32_e32 v65, v69, v65
	v_mul_f32_e32 v66, v70, v66
	v_mul_f32_e32 v67, v71, v67
	v_mul_f32_e32 v40, v40, v0
	v_mul_f32_e32 v41, v41, v0
	v_mul_f32_e32 v42, v42, v0
	v_mul_f32_e32 v43, v43, v0
	v_mul_f32_e32 v40, v40, v64
	v_mul_f32_e32 v41, v41, v65
	v_mul_f32_e32 v42, v42, v66
	v_mul_f32_e32 v43, v43, v67
	v_cvt_pk_bf16_f32 v40, v40, v41
	v_cvt_pk_bf16_f32 v41, v42, v43
	v_lshlrev_b32_e32 v64, 16, v166
	v_and_b32_e32 v65, 0xffff0000, v166
	v_lshlrev_b32_e32 v66, 16, v167
	v_and_b32_e32 v67, 0xffff0000, v167
	v_mul_f32_e32 v68, 0xbfb8aa3b, v64
	v_mul_f32_e32 v69, 0xbfb8aa3b, v65
	v_mul_f32_e32 v70, 0xbfb8aa3b, v66
	v_mul_f32_e32 v71, 0xbfb8aa3b, v67
	v_exp_f32_e32 v68, v68
	v_exp_f32_e32 v69, v69
	v_exp_f32_e32 v70, v70
	v_exp_f32_e32 v71, v71
	v_add_f32_e32 v68, 1.0, v68
	v_add_f32_e32 v69, 1.0, v69
	v_add_f32_e32 v70, 1.0, v70
	v_add_f32_e32 v71, 1.0, v71
	v_rcp_f32_e32 v68, v68
	v_rcp_f32_e32 v69, v69
	v_rcp_f32_e32 v70, v70
	v_rcp_f32_e32 v71, v71
	v_mul_f32_e32 v64, v68, v64
	v_mul_f32_e32 v65, v69, v65
	v_mul_f32_e32 v66, v70, v66
	v_mul_f32_e32 v67, v71, v67
	v_mul_f32_e32 v44, v44, v0
	v_mul_f32_e32 v45, v45, v0
	v_mul_f32_e32 v46, v46, v0
	v_mul_f32_e32 v47, v47, v0
	v_mul_f32_e32 v44, v44, v64
	v_mul_f32_e32 v45, v45, v65
	v_mul_f32_e32 v46, v46, v66
	v_mul_f32_e32 v47, v47, v67
	v_cvt_pk_bf16_f32 v42, v44, v45
	v_cvt_pk_bf16_f32 v43, v46, v47
	s_nop 1
	v_permlane32_swap_b32_e32 v40, v42
; DI unsigned cvtpk(float lo, float hi) { typedef float f2 __attribute__((ext_vector_type(2))); typedef __bf16 b2 __attribute__((ext_vector_type(2))); f2 v = {lo, hi}; b2 b = __builtin_convertvector(v, b2); return __builtin_bit_cast(unsigned, b); }
; DI float bflo(unsigned w) { return __uint_as_float(w << 16); }
; DI float bfhi(unsigned w) { return __uint_as_float(w & 0xffff0000u); }
; DI float silu_(float g) { return g * fast_rcp(1.f + fast_exp2(-g * LOG2E)); }
; DI void write_y(const f32x16& o0, const f32x16& o1, float scale, const bf16_t* grow, bf16_t* yrow, int h) {
; #pragma unroll
;     for (int dh = 0; dh < 2; ++dh) {
;         u32x2 w[4];
; #pragma unroll
;         for (int grp = 0; grp < 4; ++grp) {
;             const int d0 = 32 * dh + 8 * grp + 4 * h;
;             const u32x2 g = *(const u32x2*)(grow + d0);
;             const f32x16& o = dh ? o1 : o0;
;             const float y0 = o[4 * grp + 0] * scale * silu_(bflo(g.x)), y1 = o[4 * grp + 1] * scale * silu_(bfhi(g.x));
;             const float y2 = o[4 * grp + 2] * scale * silu_(bflo(g.y)), y3 = o[4 * grp + 3] * scale * silu_(bfhi(g.y));
;             w[grp].x = cvtpk(y0, y1); w[grp].y = cvtpk(y2, y3);
;         }
;         store_pair16(yrow + 32 * dh, w[0], w[1], 0, h);
;         store_pair16(yrow + 32 * dh, w[2], w[3], 1, h);
;     }
	v_permlane32_swap_b32_e32 v41, v43
	global_store_dwordx4 v[104:105], v[40:43], off offset:32 nt
	v_lshlrev_b32_e32 v64, 16, v168
	v_and_b32_e32 v65, 0xffff0000, v168
	v_lshlrev_b32_e32 v66, 16, v169
	v_and_b32_e32 v67, 0xffff0000, v169
	v_mul_f32_e32 v68, 0xbfb8aa3b, v64
	v_mul_f32_e32 v69, 0xbfb8aa3b, v65
	v_mul_f32_e32 v70, 0xbfb8aa3b, v66
	v_mul_f32_e32 v71, 0xbfb8aa3b, v67
	v_exp_f32_e32 v68, v68
	v_exp_f32_e32 v69, v69
	v_exp_f32_e32 v70, v70
	v_exp_f32_e32 v71, v71
	v_add_f32_e32 v68, 1.0, v68
	v_add_f32_e32 v69, 1.0, v69
	v_add_f32_e32 v70, 1.0, v70
	v_add_f32_e32 v71, 1.0, v71
	v_rcp_f32_e32 v68, v68
	v_rcp_f32_e32 v69, v69
	v_rcp_f32_e32 v70, v70
	v_rcp_f32_e32 v71, v71
	v_mul_f32_e32 v64, v68, v64
	v_mul_f32_e32 v65, v69, v65
	v_mul_f32_e32 v66, v70, v66
	v_mul_f32_e32 v67, v71, v67
	v_mul_f32_e32 v16, v16, v0
	v_mul_f32_e32 v17, v17, v0
	v_mul_f32_e32 v18, v18, v0
	v_mul_f32_e32 v19, v19, v0
	v_mul_f32_e32 v16, v16, v64
	v_mul_f32_e32 v17, v17, v65
	v_mul_f32_e32 v18, v18, v66
	v_mul_f32_e32 v19, v19, v67
	v_cvt_pk_bf16_f32 v16, v16, v17
	v_cvt_pk_bf16_f32 v17, v18, v19
	v_lshlrev_b32_e32 v64, 16, v170
	v_and_b32_e32 v65, 0xffff0000, v170
	v_lshlrev_b32_e32 v66, 16, v171
	v_and_b32_e32 v67, 0xffff0000, v171
	v_mul_f32_e32 v68, 0xbfb8aa3b, v64
	v_mul_f32_e32 v69, 0xbfb8aa3b, v65
	v_mul_f32_e32 v70, 0xbfb8aa3b, v66
	v_mul_f32_e32 v71, 0xbfb8aa3b, v67
	v_exp_f32_e32 v68, v68
	v_exp_f32_e32 v69, v69
	v_exp_f32_e32 v70, v70
	v_exp_f32_e32 v71, v71
	v_add_f32_e32 v68, 1.0, v68
	v_add_f32_e32 v69, 1.0, v69
	v_add_f32_e32 v70, 1.0, v70
	v_add_f32_e32 v71, 1.0, v71
	v_rcp_f32_e32 v68, v68
	v_rcp_f32_e32 v69, v69
	v_rcp_f32_e32 v70, v70
	v_rcp_f32_e32 v71, v71
	v_mul_f32_e32 v64, v68, v64
	v_mul_f32_e32 v65, v69, v65
	v_mul_f32_e32 v66, v70, v66
	v_mul_f32_e32 v67, v71, v67
	v_mul_f32_e32 v20, v20, v0
	v_mul_f32_e32 v21, v21, v0
	v_mul_f32_e32 v22, v22, v0
	v_mul_f32_e32 v23, v23, v0
	v_mul_f32_e32 v20, v20, v64
	v_mul_f32_e32 v21, v21, v65
	v_mul_f32_e32 v22, v22, v66
	v_mul_f32_e32 v23, v23, v67
	v_cvt_pk_bf16_f32 v18, v20, v21
	v_cvt_pk_bf16_f32 v19, v22, v23
	s_nop 1
	v_permlane32_swap_b32_e32 v16, v18
	v_permlane32_swap_b32_e32 v17, v19
	global_store_dwordx4 v[104:105], v[16:19], off offset:64 nt
	v_lshlrev_b32_e32 v64, 16, v172
	v_and_b32_e32 v65, 0xffff0000, v172
	v_lshlrev_b32_e32 v66, 16, v173
	v_and_b32_e32 v67, 0xffff0000, v173
	v_mul_f32_e32 v68, 0xbfb8aa3b, v64
	v_mul_f32_e32 v69, 0xbfb8aa3b, v65
	v_mul_f32_e32 v70, 0xbfb8aa3b, v66
	v_mul_f32_e32 v71, 0xbfb8aa3b, v67
	v_exp_f32_e32 v68, v68
	v_exp_f32_e32 v69, v69
	v_exp_f32_e32 v70, v70
	v_exp_f32_e32 v71, v71
	v_add_f32_e32 v68, 1.0, v68
	v_add_f32_e32 v69, 1.0, v69
	v_add_f32_e32 v70, 1.0, v70
	v_add_f32_e32 v71, 1.0, v71
	v_rcp_f32_e32 v68, v68
	v_rcp_f32_e32 v69, v69
	v_rcp_f32_e32 v70, v70
	v_rcp_f32_e32 v71, v71
	v_mul_f32_e32 v64, v68, v64
	v_mul_f32_e32 v65, v69, v65
	v_mul_f32_e32 v66, v70, v66
	v_mul_f32_e32 v67, v71, v67
	v_mul_f32_e32 v24, v24, v0
	v_mul_f32_e32 v25, v25, v0
	v_mul_f32_e32 v26, v26, v0
	v_mul_f32_e32 v27, v27, v0
	v_mul_f32_e32 v24, v24, v64
	v_mul_f32_e32 v25, v25, v65
	v_mul_f32_e32 v26, v26, v66
	v_mul_f32_e32 v27, v27, v67
	v_cvt_pk_bf16_f32 v24, v24, v25
	v_cvt_pk_bf16_f32 v25, v26, v27
	v_lshlrev_b32_e32 v64, 16, v174
	v_and_b32_e32 v65, 0xffff0000, v174
	v_lshlrev_b32_e32 v66, 16, v175
	v_and_b32_e32 v67, 0xffff0000, v175
	v_mul_f32_e32 v68, 0xbfb8aa3b, v64
	v_mul_f32_e32 v69, 0xbfb8aa3b, v65
	v_mul_f32_e32 v70, 0xbfb8aa3b, v66
	v_mul_f32_e32 v71, 0xbfb8aa3b, v67
	v_exp_f32_e32 v68, v68
	v_exp_f32_e32 v69, v69
	v_exp_f32_e32 v70, v70
	v_exp_f32_e32 v71, v71
	v_add_f32_e32 v68, 1.0, v68
	v_add_f32_e32 v69, 1.0, v69
	v_add_f32_e32 v70, 1.0, v70
	v_add_f32_e32 v71, 1.0, v71
	v_rcp_f32_e32 v68, v68
	v_rcp_f32_e32 v69, v69
	v_rcp_f32_e32 v70, v70
	v_rcp_f32_e32 v71, v71
	v_mul_f32_e32 v64, v68, v64
	v_mul_f32_e32 v65, v69, v65
	v_mul_f32_e32 v66, v70, v66
	v_mul_f32_e32 v67, v71, v67
	v_mul_f32_e32 v28, v28, v0
	v_mul_f32_e32 v29, v29, v0
	v_mul_f32_e32 v30, v30, v0
	v_mul_f32_e32 v31, v31, v0
	v_mul_f32_e32 v28, v28, v64
	v_mul_f32_e32 v29, v29, v65
	v_mul_f32_e32 v30, v30, v66
	v_mul_f32_e32 v31, v31, v67
	v_cvt_pk_bf16_f32 v26, v28, v29
	v_cvt_pk_bf16_f32 v27, v30, v31
	s_nop 1
	v_permlane32_swap_b32_e32 v24, v26
	v_permlane32_swap_b32_e32 v25, v27
	global_store_dwordx4 v[104:105], v[24:27], off offset:96 nt
	s_cbranch_scc1 .LBB0_360
